# GEMM K-loops: first iteration peeled with C=0 on first-touch MFMAs, 128 accumulator-clear v_movs per unit removed
# speedup vs baseline: 1.0116x; 1.0116x over previous
.LBB0_159:
	s_ashr_i32 s29, s28, 31
	s_lshl_b64 s[24:25], s[28:29], 19
	s_add_u32 s24, s34, s24
	s_addc_u32 s25, s35, s25
	s_and_b64 s[30:31], s[18:19], exec
	s_cselect_b32 s29, s25, s41
	s_cselect_b32 s43, s24, s40
	s_ashr_i32 s21, s20, 31
	s_lshl_b64 s[30:31], s[20:21], 19
	s_add_u32 s30, s36, s30
	s_addc_u32 s31, s37, s31
	s_and_b64 s[56:57], s[18:19], exec
	s_cselect_b32 s21, s31, s27
	s_cselect_b32 s55, s30, s26
	s_add_u32 s40, s40, 0x40080
	s_addc_u32 s41, s41, 0
	s_add_u32 s56, s26, 0x100
	s_addc_u32 s57, s27, 0
	s_mov_b32 s58, -2
	s_add_u32 s26, s40, 0xfffc0080
	s_addc_u32 s27, s41, -1
	s_add_i32 s59, 0, 0x10000
	s_cmp_eq_u32 s58, 12
	s_cselect_b32 vcc_hi, s29, s27
	s_cselect_b32 vcc_lo, s43, s26
	v_add_u32_e32 v0, s59, v167
	s_cselect_b32 s27, s21, s57
	s_cselect_b32 s26, s55, s56
	s_add_i32 s62, 0, 0x14000
	ds_read_b128 v[142:145], v0
	ds_read_b128 v[146:149], v0 offset:1024
	ds_read_b128 v[150:153], v0 offset:2048
	ds_read_b128 v[154:157], v0 offset:3072
	v_add_u32_e32 v0, s62, v167
	ds_read_b128 v[158:161], v0
	ds_read_b128 v[162:165], v0 offset:1024
	ds_read_b128 v[174:177], v0 offset:2048
	ds_read_b128 v[178:181], v0 offset:3072
	v_lshl_add_u64 v[214:215], s[40:41], 0, v[138:139]
	s_add_i32 m0, s23, 0xc000
	ds_read_b128 v[182:185], v173
	ds_read_b128 v[186:189], v173 offset:1024
	ds_read_b128 v[190:193], v173 offset:2048
	ds_read_b128 v[194:197], v173 offset:3072
	ds_read_b128 v[198:201], v173 offset:4096
	ds_read_b128 v[202:205], v173 offset:5120
	ds_read_b128 v[206:209], v173 offset:6144
	ds_read_b128 v[210:213], v173 offset:7168
	global_load_lds_dwordx4 v[214:215], off
	v_lshl_add_u64 v[214:215], s[40:41], 0, v[140:141]
	s_add_i32 m0, s23, 0xe000
	s_nop 0
	global_load_lds_dwordx4 v[214:215], off
	s_waitcnt vmcnt(8)
	s_waitcnt lgkmcnt(0)
	s_barrier
	s_setprio 1
	s_waitcnt lgkmcnt(0)
	v_mfma_f32_16x16x32_bf16 v[126:129], v[142:145], v[182:185], 0
	v_mfma_f32_16x16x32_bf16 v[122:125], v[150:153], v[182:185], 0
	v_mfma_f32_16x16x32_bf16 v[118:121], v[142:145], v[190:193], 0
	v_mfma_f32_16x16x32_bf16 v[114:117], v[150:153], v[190:193], 0
	v_mfma_f32_16x16x32_bf16 v[110:113], v[142:145], v[198:201], 0
	v_mfma_f32_16x16x32_bf16 v[106:109], v[150:153], v[198:201], 0
	v_mfma_f32_16x16x32_bf16 v[102:105], v[142:145], v[206:209], 0
	v_mfma_f32_16x16x32_bf16 v[98:101], v[150:153], v[206:209], 0
	v_mfma_f32_16x16x32_bf16 v[126:129], v[146:149], v[186:189], v[126:129]
	v_mfma_f32_16x16x32_bf16 v[122:125], v[154:157], v[186:189], v[122:125]
	v_mfma_f32_16x16x32_bf16 v[118:121], v[146:149], v[194:197], v[118:121]
	v_mfma_f32_16x16x32_bf16 v[114:117], v[154:157], v[194:197], v[114:117]
	v_mfma_f32_16x16x32_bf16 v[110:113], v[146:149], v[202:205], v[110:113]
	v_mfma_f32_16x16x32_bf16 v[106:109], v[154:157], v[202:205], v[106:109]
	v_mfma_f32_16x16x32_bf16 v[102:105], v[146:149], v[210:213], v[102:105]
	v_mfma_f32_16x16x32_bf16 v[98:101], v[154:157], v[210:213], v[98:101]
	s_setprio 0
	s_setprio 1
	v_mfma_f32_16x16x32_bf16 v[82:85], v[158:161], v[182:185], 0
	v_mfma_f32_16x16x32_bf16 v[74:77], v[174:177], v[182:185], 0
	v_mfma_f32_16x16x32_bf16 v[70:73], v[158:161], v[190:193], 0
	v_mfma_f32_16x16x32_bf16 v[62:65], v[174:177], v[190:193], 0
	v_mfma_f32_16x16x32_bf16 v[54:57], v[158:161], v[198:201], 0
	v_mfma_f32_16x16x32_bf16 v[46:49], v[174:177], v[198:201], 0
	v_mfma_f32_16x16x32_bf16 v[38:41], v[158:161], v[206:209], 0
	v_mfma_f32_16x16x32_bf16 v[34:37], v[174:177], v[206:209], 0
	v_mfma_f32_16x16x32_bf16 v[82:85], v[162:165], v[186:189], v[82:85]
	v_mfma_f32_16x16x32_bf16 v[74:77], v[178:181], v[186:189], v[74:77]
	v_mfma_f32_16x16x32_bf16 v[70:73], v[162:165], v[194:197], v[70:73]
	v_mfma_f32_16x16x32_bf16 v[62:65], v[178:181], v[194:197], v[62:65]
	v_mfma_f32_16x16x32_bf16 v[54:57], v[162:165], v[202:205], v[54:57]
	v_mfma_f32_16x16x32_bf16 v[46:49], v[178:181], v[202:205], v[46:49]
	v_mfma_f32_16x16x32_bf16 v[38:41], v[162:165], v[210:213], v[38:41]
	v_mfma_f32_16x16x32_bf16 v[34:37], v[178:181], v[210:213], v[34:37]
	s_setprio 0
	s_barrier
	s_add_i32 s59, s59, s44
	v_lshl_add_u64 v[214:215], s[26:27], 0, v[132:133]
	s_mov_b32 m0, s59
	ds_read_b128 v[182:185], v173 offset:16384
	ds_read_b128 v[186:189], v173 offset:17408
	ds_read_b128 v[190:193], v173 offset:18432
	ds_read_b128 v[194:197], v173 offset:19456
	ds_read_b128 v[198:201], v173 offset:20480
	ds_read_b128 v[202:205], v173 offset:21504
	ds_read_b128 v[206:209], v173 offset:22528
	ds_read_b128 v[210:213], v173 offset:23552
	global_load_lds_dwordx4 v[214:215], off
	s_add_i32 m0, s59, 0x2000
	s_add_u32 s60, s26, 0x40000
	v_lshl_add_u64 v[216:217], s[26:27], 0, v[136:137]
	s_addc_u32 s61, s27, 0
	s_add_i32 s59, s62, s44
	global_load_lds_dwordx4 v[216:217], off
	v_lshl_add_u64 v[218:219], s[60:61], 0, v[132:133]
	s_mov_b32 m0, s59
	v_lshl_add_u64 v[220:221], vcc, 0, v[134:135]
	global_load_lds_dwordx4 v[218:219], off
	v_lshl_add_u64 v[218:219], s[60:61], 0, v[136:137]
	s_add_i32 m0, s59, 0x2000
	s_nop 0
	global_load_lds_dwordx4 v[218:219], off
	v_lshl_add_u64 v[218:219], vcc, 0, v[130:131]
	s_mov_b32 m0, s23
	s_nop 0
	global_load_lds_dwordx4 v[218:219], off
	s_mov_b32 m0, s45
	s_nop 0
	global_load_lds_dwordx4 v[220:221], off
	s_waitcnt vmcnt(8)
	s_waitcnt lgkmcnt(0)
	s_barrier
	s_setprio 1
	s_waitcnt lgkmcnt(0)
	v_mfma_f32_16x16x32_bf16 v[94:97], v[142:145], v[182:185], 0
	v_mfma_f32_16x16x32_bf16 v[90:93], v[150:153], v[182:185], 0
	v_mfma_f32_16x16x32_bf16 v[86:89], v[142:145], v[190:193], 0
	v_mfma_f32_16x16x32_bf16 v[78:81], v[150:153], v[190:193], 0
	v_mfma_f32_16x16x32_bf16 v[66:69], v[142:145], v[198:201], 0
	v_mfma_f32_16x16x32_bf16 v[58:61], v[150:153], v[198:201], 0
	v_mfma_f32_16x16x32_bf16 v[50:53], v[142:145], v[206:209], 0
	v_mfma_f32_16x16x32_bf16 v[42:45], v[150:153], v[206:209], 0
	v_mfma_f32_16x16x32_bf16 v[94:97], v[146:149], v[186:189], v[94:97]
	v_mfma_f32_16x16x32_bf16 v[90:93], v[154:157], v[186:189], v[90:93]
	v_mfma_f32_16x16x32_bf16 v[86:89], v[146:149], v[194:197], v[86:89]
	v_mfma_f32_16x16x32_bf16 v[78:81], v[154:157], v[194:197], v[78:81]
	v_mfma_f32_16x16x32_bf16 v[66:69], v[146:149], v[202:205], v[66:69]
	v_mfma_f32_16x16x32_bf16 v[58:61], v[154:157], v[202:205], v[58:61]
	v_mfma_f32_16x16x32_bf16 v[50:53], v[146:149], v[210:213], v[50:53]
	v_mfma_f32_16x16x32_bf16 v[42:45], v[154:157], v[210:213], v[42:45]
	s_setprio 0
	s_setprio 1
	v_mfma_f32_16x16x32_bf16 v[30:33], v[158:161], v[182:185], 0
	v_mfma_f32_16x16x32_bf16 v[26:29], v[174:177], v[182:185], 0
	v_mfma_f32_16x16x32_bf16 v[22:25], v[158:161], v[190:193], 0
	v_mfma_f32_16x16x32_bf16 v[18:21], v[174:177], v[190:193], 0
	v_mfma_f32_16x16x32_bf16 v[14:17], v[158:161], v[198:201], 0
	v_mfma_f32_16x16x32_bf16 v[10:13], v[174:177], v[198:201], 0
	v_mfma_f32_16x16x32_bf16 v[6:9], v[158:161], v[206:209], 0
	v_mfma_f32_16x16x32_bf16 v[2:5], v[174:177], v[206:209], 0
	v_mfma_f32_16x16x32_bf16 v[30:33], v[162:165], v[186:189], v[30:33]
	v_mfma_f32_16x16x32_bf16 v[26:29], v[178:181], v[186:189], v[26:29]
	v_mfma_f32_16x16x32_bf16 v[22:25], v[162:165], v[194:197], v[22:25]
	v_mfma_f32_16x16x32_bf16 v[18:21], v[178:181], v[194:197], v[18:21]
	v_mfma_f32_16x16x32_bf16 v[14:17], v[162:165], v[202:205], v[14:17]
	v_mfma_f32_16x16x32_bf16 v[10:13], v[178:181], v[202:205], v[10:13]
	v_mfma_f32_16x16x32_bf16 v[6:9], v[162:165], v[210:213], v[6:9]
	v_mfma_f32_16x16x32_bf16 v[2:5], v[178:181], v[210:213], v[2:5]
	s_setprio 0
	s_barrier
	s_add_i32 s59, 0, 0x18000
	v_add_u32_e32 v0, s59, v167
	s_add_i32 s62, 0, 0x1c000
	ds_read_b128 v[142:145], v0
	ds_read_b128 v[146:149], v0 offset:1024
	ds_read_b128 v[150:153], v0 offset:2048
	ds_read_b128 v[154:157], v0 offset:3072
	v_add_u32_e32 v0, s62, v167
	ds_read_b128 v[158:161], v0
	ds_read_b128 v[162:165], v0 offset:1024
	ds_read_b128 v[174:177], v0 offset:2048
	ds_read_b128 v[178:181], v0 offset:3072
	s_add_u32 s60, vcc_lo, 0x40000
	s_addc_u32 s61, vcc_hi, 0
	s_mov_b32 m0, s47
	v_lshl_add_u64 v[222:223], s[60:61], 0, v[130:131]
	ds_read_b128 v[182:185], v173 offset:32768
	ds_read_b128 v[186:189], v173 offset:33792
	ds_read_b128 v[190:193], v173 offset:34816
	ds_read_b128 v[194:197], v173 offset:35840
	ds_read_b128 v[198:201], v173 offset:36864
	ds_read_b128 v[202:205], v173 offset:37888
	ds_read_b128 v[206:209], v173 offset:38912
	ds_read_b128 v[210:213], v173 offset:39936
	global_load_lds_dwordx4 v[222:223], off
	v_lshl_add_u64 v[222:223], s[60:61], 0, v[134:135]
	s_mov_b32 m0, s49
	s_nop 0
	global_load_lds_dwordx4 v[222:223], off
	s_waitcnt vmcnt(8)
	s_waitcnt lgkmcnt(0)
	s_barrier
	s_setprio 1
	s_waitcnt lgkmcnt(0)
	v_mfma_f32_16x16x32_bf16 v[126:129], v[142:145], v[182:185], v[126:129]
	v_mfma_f32_16x16x32_bf16 v[122:125], v[150:153], v[182:185], v[122:125]
	v_mfma_f32_16x16x32_bf16 v[118:121], v[142:145], v[190:193], v[118:121]
	v_mfma_f32_16x16x32_bf16 v[114:117], v[150:153], v[190:193], v[114:117]
	v_mfma_f32_16x16x32_bf16 v[110:113], v[142:145], v[198:201], v[110:113]
	v_mfma_f32_16x16x32_bf16 v[106:109], v[150:153], v[198:201], v[106:109]
	v_mfma_f32_16x16x32_bf16 v[102:105], v[142:145], v[206:209], v[102:105]
	v_mfma_f32_16x16x32_bf16 v[98:101], v[150:153], v[206:209], v[98:101]
	v_mfma_f32_16x16x32_bf16 v[126:129], v[146:149], v[186:189], v[126:129]
	v_mfma_f32_16x16x32_bf16 v[122:125], v[154:157], v[186:189], v[122:125]
	v_mfma_f32_16x16x32_bf16 v[118:121], v[146:149], v[194:197], v[118:121]
	v_mfma_f32_16x16x32_bf16 v[114:117], v[154:157], v[194:197], v[114:117]
	v_mfma_f32_16x16x32_bf16 v[110:113], v[146:149], v[202:205], v[110:113]
	v_mfma_f32_16x16x32_bf16 v[106:109], v[154:157], v[202:205], v[106:109]
	v_mfma_f32_16x16x32_bf16 v[102:105], v[146:149], v[210:213], v[102:105]
	v_mfma_f32_16x16x32_bf16 v[98:101], v[154:157], v[210:213], v[98:101]
	s_setprio 0
	s_setprio 1
	v_mfma_f32_16x16x32_bf16 v[82:85], v[158:161], v[182:185], v[82:85]
	v_mfma_f32_16x16x32_bf16 v[74:77], v[174:177], v[182:185], v[74:77]
	v_mfma_f32_16x16x32_bf16 v[70:73], v[158:161], v[190:193], v[70:73]
	v_mfma_f32_16x16x32_bf16 v[62:65], v[174:177], v[190:193], v[62:65]
	v_mfma_f32_16x16x32_bf16 v[54:57], v[158:161], v[198:201], v[54:57]
	v_mfma_f32_16x16x32_bf16 v[46:49], v[174:177], v[198:201], v[46:49]
	v_mfma_f32_16x16x32_bf16 v[38:41], v[158:161], v[206:209], v[38:41]
	v_mfma_f32_16x16x32_bf16 v[34:37], v[174:177], v[206:209], v[34:37]
	v_mfma_f32_16x16x32_bf16 v[82:85], v[162:165], v[186:189], v[82:85]
	v_mfma_f32_16x16x32_bf16 v[74:77], v[178:181], v[186:189], v[74:77]
	v_mfma_f32_16x16x32_bf16 v[70:73], v[162:165], v[194:197], v[70:73]
	v_mfma_f32_16x16x32_bf16 v[62:65], v[178:181], v[194:197], v[62:65]
	v_mfma_f32_16x16x32_bf16 v[54:57], v[162:165], v[202:205], v[54:57]
	v_mfma_f32_16x16x32_bf16 v[46:49], v[178:181], v[202:205], v[46:49]
	v_mfma_f32_16x16x32_bf16 v[38:41], v[162:165], v[210:213], v[38:41]
	v_mfma_f32_16x16x32_bf16 v[34:37], v[178:181], v[210:213], v[34:37]
	s_setprio 0
	s_barrier
	s_add_i32 s59, s59, s44
	v_lshl_add_u64 v[214:215], v[214:215], 0, s[98:99]
	s_mov_b32 m0, s59
	ds_read_b128 v[182:185], v173 offset:49152
	ds_read_b128 v[186:189], v173 offset:50176
	ds_read_b128 v[190:193], v173 offset:51200
	ds_read_b128 v[194:197], v173 offset:52224
	ds_read_b128 v[198:201], v173 offset:53248
	ds_read_b128 v[202:205], v173 offset:54272
	ds_read_b128 v[206:209], v173 offset:55296
	ds_read_b128 v[210:213], v173 offset:56320
	global_load_lds_dwordx4 v[214:215], off
	s_add_i32 m0, s59, 0x2000
	s_add_u32 s26, s26, 0x40080
	v_lshl_add_u64 v[214:215], v[216:217], 0, s[98:99]
	s_addc_u32 s27, s27, 0
	s_add_i32 s59, s62, s44
	global_load_lds_dwordx4 v[214:215], off
	v_lshl_add_u64 v[214:215], s[26:27], 0, v[132:133]
	s_mov_b32 m0, s59
	s_nop 0
	global_load_lds_dwordx4 v[214:215], off
	v_lshl_add_u64 v[214:215], s[26:27], 0, v[136:137]
	s_add_i32 m0, s59, 0x2000
	s_nop 0
	global_load_lds_dwordx4 v[214:215], off
	v_lshl_add_u64 v[214:215], v[218:219], 0, s[98:99]
	s_mov_b32 m0, s52
	s_nop 0
	global_load_lds_dwordx4 v[214:215], off
	v_lshl_add_u64 v[214:215], v[220:221], 0, s[98:99]
	s_mov_b32 m0, s53
	s_nop 0
	global_load_lds_dwordx4 v[214:215], off
	s_waitcnt vmcnt(8)
	s_waitcnt lgkmcnt(0)
	s_barrier
	s_setprio 1
	s_waitcnt lgkmcnt(0)
	v_mfma_f32_16x16x32_bf16 v[94:97], v[142:145], v[182:185], v[94:97]
	v_mfma_f32_16x16x32_bf16 v[90:93], v[150:153], v[182:185], v[90:93]
	v_mfma_f32_16x16x32_bf16 v[86:89], v[142:145], v[190:193], v[86:89]
	v_mfma_f32_16x16x32_bf16 v[78:81], v[150:153], v[190:193], v[78:81]
	v_mfma_f32_16x16x32_bf16 v[66:69], v[142:145], v[198:201], v[66:69]
	v_mfma_f32_16x16x32_bf16 v[58:61], v[150:153], v[198:201], v[58:61]
	v_mfma_f32_16x16x32_bf16 v[50:53], v[142:145], v[206:209], v[50:53]
	v_mfma_f32_16x16x32_bf16 v[42:45], v[150:153], v[206:209], v[42:45]
	v_mfma_f32_16x16x32_bf16 v[94:97], v[146:149], v[186:189], v[94:97]
	v_mfma_f32_16x16x32_bf16 v[90:93], v[154:157], v[186:189], v[90:93]
	v_mfma_f32_16x16x32_bf16 v[86:89], v[146:149], v[194:197], v[86:89]
	v_mfma_f32_16x16x32_bf16 v[78:81], v[154:157], v[194:197], v[78:81]
	v_mfma_f32_16x16x32_bf16 v[66:69], v[146:149], v[202:205], v[66:69]
	v_mfma_f32_16x16x32_bf16 v[58:61], v[154:157], v[202:205], v[58:61]
	v_mfma_f32_16x16x32_bf16 v[50:53], v[146:149], v[210:213], v[50:53]
	v_mfma_f32_16x16x32_bf16 v[42:45], v[154:157], v[210:213], v[42:45]
	s_setprio 0
	s_setprio 1
	v_mfma_f32_16x16x32_bf16 v[30:33], v[158:161], v[182:185], v[30:33]
	v_mfma_f32_16x16x32_bf16 v[26:29], v[174:177], v[182:185], v[26:29]
	v_mfma_f32_16x16x32_bf16 v[22:25], v[158:161], v[190:193], v[22:25]
	v_mfma_f32_16x16x32_bf16 v[18:21], v[174:177], v[190:193], v[18:21]
	v_mfma_f32_16x16x32_bf16 v[14:17], v[158:161], v[198:201], v[14:17]
	v_mfma_f32_16x16x32_bf16 v[10:13], v[174:177], v[198:201], v[10:13]
	v_mfma_f32_16x16x32_bf16 v[6:9], v[158:161], v[206:209], v[6:9]
	v_mfma_f32_16x16x32_bf16 v[2:5], v[174:177], v[206:209], v[2:5]
	v_mfma_f32_16x16x32_bf16 v[30:33], v[162:165], v[186:189], v[30:33]
	v_mfma_f32_16x16x32_bf16 v[26:29], v[178:181], v[186:189], v[26:29]
	v_mfma_f32_16x16x32_bf16 v[22:25], v[162:165], v[194:197], v[22:25]
	v_mfma_f32_16x16x32_bf16 v[18:21], v[178:181], v[194:197], v[18:21]
	v_mfma_f32_16x16x32_bf16 v[14:17], v[162:165], v[202:205], v[14:17]
	v_mfma_f32_16x16x32_bf16 v[10:13], v[178:181], v[202:205], v[10:13]
	v_mfma_f32_16x16x32_bf16 v[6:9], v[162:165], v[210:213], v[6:9]
	v_mfma_f32_16x16x32_bf16 v[2:5], v[178:181], v[210:213], v[2:5]
	s_setprio 0
	s_barrier
	s_add_i32 s58, s58, 2
	s_add_u32 s40, s40, 0x100
	s_addc_u32 s41, s41, 0
	s_add_u32 s56, s56, 0x100
	s_addc_u32 s57, s57, 0
	s_cmp_gt_u32 s58, 13
	s_cbranch_scc1 .Lpeel_done_160

.Lpeel_done_160:
	s_and_b64 vcc, exec, s[14:15]
	s_cbranch_vccz .LBB0_163
	s_barrier

.LBB0_216:
	s_add_i32 s13, s61, -2
	s_add_u32 s28, s28, 0x80
	s_addc_u32 s29, s29, 0
	s_add_u32 s23, s40, 0x100
	s_addc_u32 s40, s41, 0
	s_mov_b32 s30, 0
	s_add_i32 s41, s30, 2
	s_add_u32 vcc_lo, s28, 0x80
	s_addc_u32 s31, s29, 0
	s_add_i32 s62, 0, 0x10000
	s_cmp_eq_u32 s13, s30
	s_cselect_b32 s31, s25, s31
	s_cselect_b32 s30, s24, vcc_lo
	v_add_u32_e32 v145, s62, v175
	s_cselect_b32 vcc_hi, s27, s40
	s_cselect_b32 vcc_lo, s26, s23
	s_add_i32 s63, 0, 0x14000
	ds_read_b128 v[130:133], v145
	ds_read_b128 v[134:137], v145 offset:1024
	ds_read_b128 v[152:155], v145 offset:2048
	ds_read_b128 v[156:159], v145 offset:3072
	v_add_u32_e32 v145, s63, v175
	ds_read_b128 v[160:163], v145
	ds_read_b128 v[164:167], v145 offset:1024
	ds_read_b128 v[168:171], v145 offset:2048
	ds_read_b128 v[186:189], v145 offset:3072
	v_lshl_add_u64 v[172:173], s[28:29], 0, v[148:149]
	s_add_i32 m0, s93, 0xc000
	ds_read_b128 v[190:193], v184
	ds_read_b128 v[194:197], v184 offset:1024
	ds_read_b128 v[198:201], v184 offset:2048
	ds_read_b128 v[202:205], v184 offset:3072
	ds_read_b128 v[206:209], v184 offset:4096
	ds_read_b128 v[210:213], v184 offset:5120
	ds_read_b128 v[214:217], v184 offset:6144
	ds_read_b128 v[218:221], v184 offset:7168
	global_load_lds_dwordx4 v[172:173], off
	v_lshl_add_u64 v[172:173], s[28:29], 0, v[150:151]
	s_add_i32 m0, s93, 0xe000
	s_nop 0
	global_load_lds_dwordx4 v[172:173], off
	s_waitcnt vmcnt(8)
	s_waitcnt lgkmcnt(0)
	s_barrier
	s_setprio 1
	s_waitcnt lgkmcnt(0)
	v_mfma_f32_16x16x32_bf16 v[126:129], v[130:133], v[190:193], 0
	v_mfma_f32_16x16x32_bf16 v[122:125], v[152:155], v[190:193], 0
	v_mfma_f32_16x16x32_bf16 v[110:113], v[130:133], v[198:201], 0
	v_mfma_f32_16x16x32_bf16 v[106:109], v[152:155], v[198:201], 0
	v_mfma_f32_16x16x32_bf16 v[94:97], v[130:133], v[206:209], 0
	v_mfma_f32_16x16x32_bf16 v[90:93], v[152:155], v[206:209], 0
	v_mfma_f32_16x16x32_bf16 v[78:81], v[130:133], v[214:217], 0
	v_mfma_f32_16x16x32_bf16 v[74:77], v[152:155], v[214:217], 0
	v_mfma_f32_16x16x32_bf16 v[126:129], v[134:137], v[194:197], v[126:129]
	v_mfma_f32_16x16x32_bf16 v[122:125], v[156:159], v[194:197], v[122:125]
	v_mfma_f32_16x16x32_bf16 v[110:113], v[134:137], v[202:205], v[110:113]
	v_mfma_f32_16x16x32_bf16 v[106:109], v[156:159], v[202:205], v[106:109]
	v_mfma_f32_16x16x32_bf16 v[94:97], v[134:137], v[210:213], v[94:97]
	v_mfma_f32_16x16x32_bf16 v[90:93], v[156:159], v[210:213], v[90:93]
	v_mfma_f32_16x16x32_bf16 v[78:81], v[134:137], v[218:221], v[78:81]
	v_mfma_f32_16x16x32_bf16 v[74:77], v[156:159], v[218:221], v[74:77]
	s_setprio 0
	s_setprio 1
	v_mfma_f32_16x16x32_bf16 v[118:121], v[160:163], v[190:193], 0
	v_mfma_f32_16x16x32_bf16 v[114:117], v[168:171], v[190:193], 0
	v_mfma_f32_16x16x32_bf16 v[102:105], v[160:163], v[198:201], 0
	v_mfma_f32_16x16x32_bf16 v[98:101], v[168:171], v[198:201], 0
	v_mfma_f32_16x16x32_bf16 v[86:89], v[160:163], v[206:209], 0
	v_mfma_f32_16x16x32_bf16 v[82:85], v[168:171], v[206:209], 0
	v_mfma_f32_16x16x32_bf16 v[70:73], v[160:163], v[214:217], 0
	v_mfma_f32_16x16x32_bf16 v[66:69], v[168:171], v[214:217], 0
	v_mfma_f32_16x16x32_bf16 v[118:121], v[164:167], v[194:197], v[118:121]
	v_mfma_f32_16x16x32_bf16 v[114:117], v[186:189], v[194:197], v[114:117]
	v_mfma_f32_16x16x32_bf16 v[102:105], v[164:167], v[202:205], v[102:105]
	v_mfma_f32_16x16x32_bf16 v[98:101], v[186:189], v[202:205], v[98:101]
	v_mfma_f32_16x16x32_bf16 v[86:89], v[164:167], v[210:213], v[86:89]
	v_mfma_f32_16x16x32_bf16 v[82:85], v[186:189], v[210:213], v[82:85]
	v_mfma_f32_16x16x32_bf16 v[70:73], v[164:167], v[218:221], v[70:73]
	v_mfma_f32_16x16x32_bf16 v[66:69], v[186:189], v[218:221], v[66:69]
	s_setprio 0
	s_barrier
	s_add_i32 s62, s62, s49
	v_lshl_add_u64 v[172:173], vcc, 0, v[0:1]
	s_mov_b32 m0, s62
	ds_read_b128 v[190:193], v184 offset:16384
	ds_read_b128 v[194:197], v184 offset:17408
	ds_read_b128 v[198:201], v184 offset:18432
	ds_read_b128 v[202:205], v184 offset:19456
	ds_read_b128 v[206:209], v184 offset:20480
	ds_read_b128 v[210:213], v184 offset:21504
	ds_read_b128 v[214:217], v184 offset:22528
	ds_read_b128 v[218:221], v184 offset:23552
	global_load_lds_dwordx4 v[172:173], off
	s_add_i32 m0, s62, 0x2000
	v_lshl_add_u64 v[222:223], vcc, 0, v[142:143]
	s_add_u32 vcc_lo, vcc_lo, s96
	s_addc_u32 vcc_hi, vcc_hi, 0
	s_add_i32 s62, s63, s49
	global_load_lds_dwordx4 v[222:223], off
	v_lshl_add_u64 v[236:237], vcc, 0, v[0:1]
	s_mov_b32 m0, s62
	v_lshl_add_u64 v[238:239], vcc, 0, v[142:143]
	global_load_lds_dwordx4 v[236:237], off
	s_add_i32 m0, s62, 0x2000
	v_lshl_add_u64 v[240:241], s[30:31], 0, v[138:139]
	global_load_lds_dwordx4 v[238:239], off
	s_mov_b32 m0, s93
	v_lshl_add_u64 v[242:243], s[30:31], 0, v[140:141]
	global_load_lds_dwordx4 v[240:241], off
	s_mov_b32 m0, s88
	s_nop 0
	global_load_lds_dwordx4 v[242:243], off
	s_waitcnt vmcnt(8)
	s_waitcnt lgkmcnt(0)
	s_barrier
	s_setprio 1
	s_waitcnt lgkmcnt(0)
	v_mfma_f32_16x16x32_bf16 v[62:65], v[130:133], v[190:193], 0
	v_mfma_f32_16x16x32_bf16 v[58:61], v[152:155], v[190:193], 0
	v_mfma_f32_16x16x32_bf16 v[46:49], v[130:133], v[198:201], 0
	v_mfma_f32_16x16x32_bf16 v[42:45], v[152:155], v[198:201], 0
	v_mfma_f32_16x16x32_bf16 v[30:33], v[130:133], v[206:209], 0
	v_mfma_f32_16x16x32_bf16 v[26:29], v[152:155], v[206:209], 0
	v_mfma_f32_16x16x32_bf16 v[14:17], v[130:133], v[214:217], 0
	v_mfma_f32_16x16x32_bf16 v[10:13], v[152:155], v[214:217], 0
	v_mfma_f32_16x16x32_bf16 v[62:65], v[134:137], v[194:197], v[62:65]
	v_mfma_f32_16x16x32_bf16 v[58:61], v[156:159], v[194:197], v[58:61]
	v_mfma_f32_16x16x32_bf16 v[46:49], v[134:137], v[202:205], v[46:49]
	v_mfma_f32_16x16x32_bf16 v[42:45], v[156:159], v[202:205], v[42:45]
	v_mfma_f32_16x16x32_bf16 v[30:33], v[134:137], v[210:213], v[30:33]
	v_mfma_f32_16x16x32_bf16 v[26:29], v[156:159], v[210:213], v[26:29]
	v_mfma_f32_16x16x32_bf16 v[14:17], v[134:137], v[218:221], v[14:17]
	v_mfma_f32_16x16x32_bf16 v[10:13], v[156:159], v[218:221], v[10:13]
	s_setprio 0
	s_setprio 1
	v_mfma_f32_16x16x32_bf16 v[54:57], v[160:163], v[190:193], 0
	v_mfma_f32_16x16x32_bf16 v[50:53], v[168:171], v[190:193], 0
	v_mfma_f32_16x16x32_bf16 v[38:41], v[160:163], v[198:201], 0
	v_mfma_f32_16x16x32_bf16 v[34:37], v[168:171], v[198:201], 0
	v_mfma_f32_16x16x32_bf16 v[22:25], v[160:163], v[206:209], 0
	v_mfma_f32_16x16x32_bf16 v[18:21], v[168:171], v[206:209], 0
	v_mfma_f32_16x16x32_bf16 v[6:9], v[160:163], v[214:217], 0
	v_mfma_f32_16x16x32_bf16 v[2:5], v[168:171], v[214:217], 0
	v_mfma_f32_16x16x32_bf16 v[54:57], v[164:167], v[194:197], v[54:57]
	v_mfma_f32_16x16x32_bf16 v[50:53], v[186:189], v[194:197], v[50:53]
	v_mfma_f32_16x16x32_bf16 v[38:41], v[164:167], v[202:205], v[38:41]
	v_mfma_f32_16x16x32_bf16 v[34:37], v[186:189], v[202:205], v[34:37]
	v_mfma_f32_16x16x32_bf16 v[22:25], v[164:167], v[210:213], v[22:25]
	v_mfma_f32_16x16x32_bf16 v[18:21], v[186:189], v[210:213], v[18:21]
	v_mfma_f32_16x16x32_bf16 v[6:9], v[164:167], v[218:221], v[6:9]
	v_mfma_f32_16x16x32_bf16 v[2:5], v[186:189], v[218:221], v[2:5]
	s_setprio 0
	s_barrier
	s_add_i32 s62, 0, 0x18000
	v_add_u32_e32 v145, s62, v175
	s_add_i32 s63, 0, 0x1c000
	ds_read_b128 v[130:133], v145
	ds_read_b128 v[134:137], v145 offset:1024
	ds_read_b128 v[152:155], v145 offset:2048
	ds_read_b128 v[156:159], v145 offset:3072
	v_add_u32_e32 v145, s63, v175
	ds_read_b128 v[160:163], v145
	ds_read_b128 v[164:167], v145 offset:1024
	ds_read_b128 v[168:171], v145 offset:2048
	ds_read_b128 v[186:189], v145 offset:3072
	s_add_u32 s30, s30, s96
	s_addc_u32 s31, s31, 0
	s_mov_b32 m0, s89
	v_lshl_add_u64 v[244:245], s[30:31], 0, v[138:139]
	ds_read_b128 v[190:193], v184 offset:32768
	ds_read_b128 v[194:197], v184 offset:33792
	ds_read_b128 v[198:201], v184 offset:34816
	ds_read_b128 v[202:205], v184 offset:35840
	ds_read_b128 v[206:209], v184 offset:36864
	ds_read_b128 v[210:213], v184 offset:37888
	ds_read_b128 v[214:217], v184 offset:38912
	ds_read_b128 v[218:221], v184 offset:39936
	global_load_lds_dwordx4 v[244:245], off
	v_lshl_add_u64 v[244:245], s[30:31], 0, v[140:141]
	s_mov_b32 m0, s52
	s_nop 0
	global_load_lds_dwordx4 v[244:245], off
	s_waitcnt vmcnt(8)
	s_waitcnt lgkmcnt(0)
	s_barrier
	s_setprio 1
	s_waitcnt lgkmcnt(0)
	v_mfma_f32_16x16x32_bf16 v[126:129], v[130:133], v[190:193], v[126:129]
	v_mfma_f32_16x16x32_bf16 v[122:125], v[152:155], v[190:193], v[122:125]
	v_mfma_f32_16x16x32_bf16 v[110:113], v[130:133], v[198:201], v[110:113]
	v_mfma_f32_16x16x32_bf16 v[106:109], v[152:155], v[198:201], v[106:109]
	v_mfma_f32_16x16x32_bf16 v[94:97], v[130:133], v[206:209], v[94:97]
	v_mfma_f32_16x16x32_bf16 v[90:93], v[152:155], v[206:209], v[90:93]
	v_mfma_f32_16x16x32_bf16 v[78:81], v[130:133], v[214:217], v[78:81]
	v_mfma_f32_16x16x32_bf16 v[74:77], v[152:155], v[214:217], v[74:77]
	v_mfma_f32_16x16x32_bf16 v[126:129], v[134:137], v[194:197], v[126:129]
	v_mfma_f32_16x16x32_bf16 v[122:125], v[156:159], v[194:197], v[122:125]
	v_mfma_f32_16x16x32_bf16 v[110:113], v[134:137], v[202:205], v[110:113]
	v_mfma_f32_16x16x32_bf16 v[106:109], v[156:159], v[202:205], v[106:109]
	v_mfma_f32_16x16x32_bf16 v[94:97], v[134:137], v[210:213], v[94:97]
	v_mfma_f32_16x16x32_bf16 v[90:93], v[156:159], v[210:213], v[90:93]
	v_mfma_f32_16x16x32_bf16 v[78:81], v[134:137], v[218:221], v[78:81]
	v_mfma_f32_16x16x32_bf16 v[74:77], v[156:159], v[218:221], v[74:77]
	s_setprio 0
	s_setprio 1
	v_mfma_f32_16x16x32_bf16 v[118:121], v[160:163], v[190:193], v[118:121]
	v_mfma_f32_16x16x32_bf16 v[114:117], v[168:171], v[190:193], v[114:117]
	v_mfma_f32_16x16x32_bf16 v[102:105], v[160:163], v[198:201], v[102:105]
	v_mfma_f32_16x16x32_bf16 v[98:101], v[168:171], v[198:201], v[98:101]
	v_mfma_f32_16x16x32_bf16 v[86:89], v[160:163], v[206:209], v[86:89]
	v_mfma_f32_16x16x32_bf16 v[82:85], v[168:171], v[206:209], v[82:85]
	v_mfma_f32_16x16x32_bf16 v[70:73], v[160:163], v[214:217], v[70:73]
	v_mfma_f32_16x16x32_bf16 v[66:69], v[168:171], v[214:217], v[66:69]
	v_mfma_f32_16x16x32_bf16 v[118:121], v[164:167], v[194:197], v[118:121]
	v_mfma_f32_16x16x32_bf16 v[114:117], v[186:189], v[194:197], v[114:117]
	v_mfma_f32_16x16x32_bf16 v[102:105], v[164:167], v[202:205], v[102:105]
	v_mfma_f32_16x16x32_bf16 v[98:101], v[186:189], v[202:205], v[98:101]
	v_mfma_f32_16x16x32_bf16 v[86:89], v[164:167], v[210:213], v[86:89]
	v_mfma_f32_16x16x32_bf16 v[82:85], v[186:189], v[210:213], v[82:85]
	v_mfma_f32_16x16x32_bf16 v[70:73], v[164:167], v[218:221], v[70:73]
	v_mfma_f32_16x16x32_bf16 v[66:69], v[186:189], v[218:221], v[66:69]
	s_setprio 0
	s_barrier
	s_add_i32 s30, s62, s49
	v_lshl_add_u64 v[172:173], v[172:173], 0, s[98:99]
	s_mov_b32 m0, s30
	ds_read_b128 v[190:193], v184 offset:49152
	ds_read_b128 v[194:197], v184 offset:50176
	ds_read_b128 v[198:201], v184 offset:51200
	ds_read_b128 v[202:205], v184 offset:52224
	ds_read_b128 v[206:209], v184 offset:53248
	ds_read_b128 v[210:213], v184 offset:54272
	ds_read_b128 v[214:217], v184 offset:55296
	ds_read_b128 v[218:221], v184 offset:56320
	global_load_lds_dwordx4 v[172:173], off
	v_lshl_add_u64 v[172:173], v[222:223], 0, s[98:99]
	s_add_i32 m0, s30, 0x2000
	s_add_i32 s30, s63, s49
	global_load_lds_dwordx4 v[172:173], off
	v_lshl_add_u64 v[172:173], v[236:237], 0, s[98:99]
	s_mov_b32 m0, s30
	s_nop 0
	global_load_lds_dwordx4 v[172:173], off
	v_lshl_add_u64 v[172:173], v[238:239], 0, s[98:99]
	s_add_i32 m0, s30, 0x2000
	s_nop 0
	global_load_lds_dwordx4 v[172:173], off
	v_lshl_add_u64 v[172:173], v[240:241], 0, s[98:99]
	s_mov_b32 m0, s95
	s_nop 0
	global_load_lds_dwordx4 v[172:173], off
	v_lshl_add_u64 v[172:173], v[242:243], 0, s[98:99]
	s_mov_b32 m0, s54
	s_nop 0
	global_load_lds_dwordx4 v[172:173], off
	s_waitcnt vmcnt(8)
	s_waitcnt lgkmcnt(0)
	s_barrier
	s_setprio 1
	s_waitcnt lgkmcnt(0)
	v_mfma_f32_16x16x32_bf16 v[62:65], v[130:133], v[190:193], v[62:65]
	v_mfma_f32_16x16x32_bf16 v[58:61], v[152:155], v[190:193], v[58:61]
	v_mfma_f32_16x16x32_bf16 v[46:49], v[130:133], v[198:201], v[46:49]
	v_mfma_f32_16x16x32_bf16 v[42:45], v[152:155], v[198:201], v[42:45]
	v_mfma_f32_16x16x32_bf16 v[30:33], v[130:133], v[206:209], v[30:33]
	v_mfma_f32_16x16x32_bf16 v[26:29], v[152:155], v[206:209], v[26:29]
	v_mfma_f32_16x16x32_bf16 v[14:17], v[130:133], v[214:217], v[14:17]
	v_mfma_f32_16x16x32_bf16 v[10:13], v[152:155], v[214:217], v[10:13]
	v_mfma_f32_16x16x32_bf16 v[62:65], v[134:137], v[194:197], v[62:65]
	v_mfma_f32_16x16x32_bf16 v[58:61], v[156:159], v[194:197], v[58:61]
	v_mfma_f32_16x16x32_bf16 v[46:49], v[134:137], v[202:205], v[46:49]
	v_mfma_f32_16x16x32_bf16 v[42:45], v[156:159], v[202:205], v[42:45]
	v_mfma_f32_16x16x32_bf16 v[30:33], v[134:137], v[210:213], v[30:33]
	v_mfma_f32_16x16x32_bf16 v[26:29], v[156:159], v[210:213], v[26:29]
	v_mfma_f32_16x16x32_bf16 v[14:17], v[134:137], v[218:221], v[14:17]
	v_mfma_f32_16x16x32_bf16 v[10:13], v[156:159], v[218:221], v[10:13]
	s_setprio 0
	s_setprio 1
	v_mfma_f32_16x16x32_bf16 v[54:57], v[160:163], v[190:193], v[54:57]
	v_mfma_f32_16x16x32_bf16 v[50:53], v[168:171], v[190:193], v[50:53]
	v_mfma_f32_16x16x32_bf16 v[38:41], v[160:163], v[198:201], v[38:41]
	v_mfma_f32_16x16x32_bf16 v[34:37], v[168:171], v[198:201], v[34:37]
	v_mfma_f32_16x16x32_bf16 v[22:25], v[160:163], v[206:209], v[22:25]
	v_mfma_f32_16x16x32_bf16 v[18:21], v[168:171], v[206:209], v[18:21]
	v_mfma_f32_16x16x32_bf16 v[6:9], v[160:163], v[214:217], v[6:9]
	v_mfma_f32_16x16x32_bf16 v[2:5], v[168:171], v[214:217], v[2:5]
	v_mfma_f32_16x16x32_bf16 v[54:57], v[164:167], v[194:197], v[54:57]
	v_mfma_f32_16x16x32_bf16 v[50:53], v[186:189], v[194:197], v[50:53]
	v_mfma_f32_16x16x32_bf16 v[38:41], v[164:167], v[202:205], v[38:41]
	v_mfma_f32_16x16x32_bf16 v[34:37], v[186:189], v[202:205], v[34:37]
	v_mfma_f32_16x16x32_bf16 v[22:25], v[164:167], v[210:213], v[22:25]
	v_mfma_f32_16x16x32_bf16 v[18:21], v[186:189], v[210:213], v[18:21]
	v_mfma_f32_16x16x32_bf16 v[6:9], v[164:167], v[218:221], v[6:9]
	v_mfma_f32_16x16x32_bf16 v[2:5], v[186:189], v[218:221], v[2:5]
	s_setprio 0
	s_barrier
	s_add_u32 s28, s28, 0x100
	s_addc_u32 s29, s29, 0
	s_add_u32 s23, s23, 0x100
	s_addc_u32 s40, s40, 0
	s_cmp_ge_i32 s41, s61
	s_mov_b32 s30, s41
	s_cbranch_scc1 .Lpeel_done_217

.Lpeel_done_217:
	s_and_b64 vcc, exec, s[18:19]
	s_cbranch_vccz .LBB0_220
	s_barrier

.LBB0_373:
	s_ashr_i32 s17, s16, 31
	s_lshl_b64 s[20:21], s[16:17], 19
	s_add_u32 s20, s37, s20
	s_addc_u32 s21, s40, s21
	s_and_b64 s[22:23], s[18:19], exec
	s_cselect_b32 s17, s21, s29
	s_cselect_b32 s25, s20, s28
	s_ashr_i32 s15, s14, 31
	s_lshl_b64 s[22:23], s[14:15], 19
	s_add_u32 s22, s41, s22
	s_addc_u32 s23, s42, s23
	s_and_b64 s[38:39], s[18:19], exec
	s_cselect_b32 s15, s23, s31
	s_cselect_b32 s53, s22, s30
	s_add_u32 s28, s28, 0x40080
	s_addc_u32 s29, s29, 0
	s_add_u32 s54, s30, 0x100
	s_addc_u32 s55, s31, 0
	s_mov_b32 s56, -2
	s_add_u32 s30, s28, 0xfffc0080
	s_addc_u32 s31, s29, -1
	s_add_i32 s57, 0, 0x10000
	s_cmp_eq_u32 s56, 12
	s_cselect_b32 s39, s17, s31
	s_cselect_b32 s38, s25, s30
	s_cselect_b32 s31, s15, s55
	s_cselect_b32 s30, s53, s54
	s_add_i32 s60, 0, 0x14000
	v_add_u32_e32 v156, s57, v145
	v_add_u32_e32 v172, s60, v145
	ds_read_b128 v[140:143], v156
	ds_read_b128 v[148:151], v156 offset:1024
	ds_read_b128 v[152:155], v156 offset:2048
	ds_read_b128 v[156:159], v156 offset:3072
	ds_read_b128 v[160:163], v172
	ds_read_b128 v[164:167], v172 offset:1024
	ds_read_b128 v[168:171], v172 offset:2048
	ds_read_b128 v[172:175], v172 offset:3072
	v_lshl_add_u64 v[208:209], s[28:29], 0, v[136:137]
	s_add_i32 m0, s27, 0xc000
	ds_read_b128 v[176:179], v147
	ds_read_b128 v[180:183], v147 offset:1024
	ds_read_b128 v[184:187], v147 offset:2048
	ds_read_b128 v[188:191], v147 offset:3072
	ds_read_b128 v[192:195], v147 offset:4096
	ds_read_b128 v[196:199], v147 offset:5120
	ds_read_b128 v[200:203], v147 offset:6144
	ds_read_b128 v[204:207], v147 offset:7168
	global_load_lds_dwordx4 v[208:209], off
	v_lshl_add_u64 v[208:209], s[28:29], 0, v[138:139]
	s_add_i32 m0, s27, 0xe000
	s_nop 0
	global_load_lds_dwordx4 v[208:209], off
	s_waitcnt vmcnt(8)
	s_waitcnt lgkmcnt(0)
	s_barrier
	s_setprio 1
	s_waitcnt lgkmcnt(0)
	v_mfma_f32_16x16x32_bf16 v[122:125], v[140:143], v[176:179], 0
	v_mfma_f32_16x16x32_bf16 v[114:117], v[152:155], v[176:179], 0
	v_mfma_f32_16x16x32_bf16 v[106:109], v[140:143], v[184:187], 0
	v_mfma_f32_16x16x32_bf16 v[98:101], v[152:155], v[184:187], 0
	v_mfma_f32_16x16x32_bf16 v[90:93], v[140:143], v[192:195], 0
	v_mfma_f32_16x16x32_bf16 v[82:85], v[152:155], v[192:195], 0
	v_mfma_f32_16x16x32_bf16 v[74:77], v[140:143], v[200:203], 0
	v_mfma_f32_16x16x32_bf16 v[66:69], v[152:155], v[200:203], 0
	v_mfma_f32_16x16x32_bf16 v[122:125], v[148:151], v[180:183], v[122:125]
	v_mfma_f32_16x16x32_bf16 v[114:117], v[156:159], v[180:183], v[114:117]
	v_mfma_f32_16x16x32_bf16 v[106:109], v[148:151], v[188:191], v[106:109]
	v_mfma_f32_16x16x32_bf16 v[98:101], v[156:159], v[188:191], v[98:101]
	v_mfma_f32_16x16x32_bf16 v[90:93], v[148:151], v[196:199], v[90:93]
	v_mfma_f32_16x16x32_bf16 v[82:85], v[156:159], v[196:199], v[82:85]
	v_mfma_f32_16x16x32_bf16 v[74:77], v[148:151], v[204:207], v[74:77]
	v_mfma_f32_16x16x32_bf16 v[66:69], v[156:159], v[204:207], v[66:69]
	s_setprio 0
	s_setprio 1
	v_mfma_f32_16x16x32_bf16 v[126:129], v[160:163], v[176:179], 0
	v_mfma_f32_16x16x32_bf16 v[118:121], v[168:171], v[176:179], 0
	v_mfma_f32_16x16x32_bf16 v[110:113], v[160:163], v[184:187], 0
	v_mfma_f32_16x16x32_bf16 v[102:105], v[168:171], v[184:187], 0
	v_mfma_f32_16x16x32_bf16 v[94:97], v[160:163], v[192:195], 0
	v_mfma_f32_16x16x32_bf16 v[86:89], v[168:171], v[192:195], 0
	v_mfma_f32_16x16x32_bf16 v[78:81], v[160:163], v[200:203], 0
	v_mfma_f32_16x16x32_bf16 v[70:73], v[168:171], v[200:203], 0
	v_mfma_f32_16x16x32_bf16 v[126:129], v[164:167], v[180:183], v[126:129]
	v_mfma_f32_16x16x32_bf16 v[118:121], v[172:175], v[180:183], v[118:121]
	v_mfma_f32_16x16x32_bf16 v[110:113], v[164:167], v[188:191], v[110:113]
	v_mfma_f32_16x16x32_bf16 v[102:105], v[172:175], v[188:191], v[102:105]
	v_mfma_f32_16x16x32_bf16 v[94:97], v[164:167], v[196:199], v[94:97]
	v_mfma_f32_16x16x32_bf16 v[86:89], v[172:175], v[196:199], v[86:89]
	v_mfma_f32_16x16x32_bf16 v[78:81], v[164:167], v[204:207], v[78:81]
	v_mfma_f32_16x16x32_bf16 v[70:73], v[172:175], v[204:207], v[70:73]
	s_setprio 0
	s_barrier
	s_add_i32 s57, s57, s43
	v_lshl_add_u64 v[208:209], s[30:31], 0, v[0:1]
	s_mov_b32 m0, s57
	ds_read_b128 v[176:179], v147 offset:16384
	ds_read_b128 v[180:183], v147 offset:17408
	ds_read_b128 v[184:187], v147 offset:18432
	ds_read_b128 v[188:191], v147 offset:19456
	ds_read_b128 v[192:195], v147 offset:20480
	ds_read_b128 v[196:199], v147 offset:21504
	ds_read_b128 v[200:203], v147 offset:22528
	ds_read_b128 v[204:207], v147 offset:23552
	global_load_lds_dwordx4 v[208:209], off
	s_add_i32 m0, s57, 0x2000
	s_add_u32 s58, s30, 0x40000
	v_lshl_add_u64 v[210:211], s[30:31], 0, v[134:135]
	s_addc_u32 s59, s31, 0
	s_add_i32 s57, s60, s43
	global_load_lds_dwordx4 v[210:211], off
	v_lshl_add_u64 v[212:213], s[58:59], 0, v[0:1]
	s_mov_b32 m0, s57
	v_lshl_add_u64 v[214:215], s[38:39], 0, v[132:133]
	global_load_lds_dwordx4 v[212:213], off
	v_lshl_add_u64 v[212:213], s[58:59], 0, v[134:135]
	s_add_i32 m0, s57, 0x2000
	s_nop 0
	global_load_lds_dwordx4 v[212:213], off
	v_lshl_add_u64 v[212:213], s[38:39], 0, v[130:131]
	s_mov_b32 m0, s27
	s_nop 0
	global_load_lds_dwordx4 v[212:213], off
	s_mov_b32 m0, s44
	s_nop 0
	global_load_lds_dwordx4 v[214:215], off
	s_waitcnt vmcnt(8)
	s_waitcnt lgkmcnt(0)
	s_barrier
	s_setprio 1
	s_waitcnt lgkmcnt(0)
	v_mfma_f32_16x16x32_bf16 v[58:61], v[140:143], v[176:179], 0
	v_mfma_f32_16x16x32_bf16 v[50:53], v[152:155], v[176:179], 0
	v_mfma_f32_16x16x32_bf16 v[42:45], v[140:143], v[184:187], 0
	v_mfma_f32_16x16x32_bf16 v[34:37], v[152:155], v[184:187], 0
	v_mfma_f32_16x16x32_bf16 v[26:29], v[140:143], v[192:195], 0
	v_mfma_f32_16x16x32_bf16 v[18:21], v[152:155], v[192:195], 0
	v_mfma_f32_16x16x32_bf16 v[10:13], v[140:143], v[200:203], 0
	v_mfma_f32_16x16x32_bf16 v[6:9], v[152:155], v[200:203], 0
	v_mfma_f32_16x16x32_bf16 v[58:61], v[148:151], v[180:183], v[58:61]
	v_mfma_f32_16x16x32_bf16 v[50:53], v[156:159], v[180:183], v[50:53]
	v_mfma_f32_16x16x32_bf16 v[42:45], v[148:151], v[188:191], v[42:45]
	v_mfma_f32_16x16x32_bf16 v[34:37], v[156:159], v[188:191], v[34:37]
	v_mfma_f32_16x16x32_bf16 v[26:29], v[148:151], v[196:199], v[26:29]
	v_mfma_f32_16x16x32_bf16 v[18:21], v[156:159], v[196:199], v[18:21]
	v_mfma_f32_16x16x32_bf16 v[10:13], v[148:151], v[204:207], v[10:13]
	v_mfma_f32_16x16x32_bf16 v[6:9], v[156:159], v[204:207], v[6:9]
	s_setprio 0
	s_setprio 1
	v_mfma_f32_16x16x32_bf16 v[62:65], v[160:163], v[176:179], 0
	v_mfma_f32_16x16x32_bf16 v[54:57], v[168:171], v[176:179], 0
	v_mfma_f32_16x16x32_bf16 v[46:49], v[160:163], v[184:187], 0
	v_mfma_f32_16x16x32_bf16 v[38:41], v[168:171], v[184:187], 0
	v_mfma_f32_16x16x32_bf16 v[30:33], v[160:163], v[192:195], 0
	v_mfma_f32_16x16x32_bf16 v[22:25], v[168:171], v[192:195], 0
	v_mfma_f32_16x16x32_bf16 v[14:17], v[160:163], v[200:203], 0
	v_mfma_f32_16x16x32_bf16 v[2:5], v[168:171], v[200:203], 0
	v_mfma_f32_16x16x32_bf16 v[62:65], v[164:167], v[180:183], v[62:65]
	v_mfma_f32_16x16x32_bf16 v[54:57], v[172:175], v[180:183], v[54:57]
	v_mfma_f32_16x16x32_bf16 v[46:49], v[164:167], v[188:191], v[46:49]
	v_mfma_f32_16x16x32_bf16 v[38:41], v[172:175], v[188:191], v[38:41]
	v_mfma_f32_16x16x32_bf16 v[30:33], v[164:167], v[196:199], v[30:33]
	v_mfma_f32_16x16x32_bf16 v[22:25], v[172:175], v[196:199], v[22:25]
	v_mfma_f32_16x16x32_bf16 v[14:17], v[164:167], v[204:207], v[14:17]
	v_mfma_f32_16x16x32_bf16 v[2:5], v[172:175], v[204:207], v[2:5]
	s_setprio 0
	s_barrier
	s_add_i32 s57, 0, 0x18000
	s_add_i32 s58, 0, 0x1c000
	v_add_u32_e32 v156, s57, v145
	v_add_u32_e32 v172, s58, v145
	ds_read_b128 v[140:143], v156
	ds_read_b128 v[148:151], v156 offset:1024
	ds_read_b128 v[152:155], v156 offset:2048
	ds_read_b128 v[156:159], v156 offset:3072
	ds_read_b128 v[160:163], v172
	ds_read_b128 v[164:167], v172 offset:1024
	ds_read_b128 v[168:171], v172 offset:2048
	ds_read_b128 v[172:175], v172 offset:3072
	s_add_u32 s38, s38, 0x40000
	s_addc_u32 s39, s39, 0
	s_mov_b32 m0, s45
	v_lshl_add_u64 v[216:217], s[38:39], 0, v[130:131]
	ds_read_b128 v[176:179], v147 offset:32768
	ds_read_b128 v[180:183], v147 offset:33792
	ds_read_b128 v[184:187], v147 offset:34816
	ds_read_b128 v[188:191], v147 offset:35840
	ds_read_b128 v[192:195], v147 offset:36864
	ds_read_b128 v[196:199], v147 offset:37888
	ds_read_b128 v[200:203], v147 offset:38912
	ds_read_b128 v[204:207], v147 offset:39936
	global_load_lds_dwordx4 v[216:217], off
	v_lshl_add_u64 v[216:217], s[38:39], 0, v[132:133]
	s_mov_b32 m0, s47
	s_nop 0
	global_load_lds_dwordx4 v[216:217], off
	s_waitcnt vmcnt(8)
	s_waitcnt lgkmcnt(0)
	s_barrier
	s_setprio 1
	s_waitcnt lgkmcnt(0)
	v_mfma_f32_16x16x32_bf16 v[122:125], v[140:143], v[176:179], v[122:125]
	v_mfma_f32_16x16x32_bf16 v[114:117], v[152:155], v[176:179], v[114:117]
	v_mfma_f32_16x16x32_bf16 v[106:109], v[140:143], v[184:187], v[106:109]
	v_mfma_f32_16x16x32_bf16 v[98:101], v[152:155], v[184:187], v[98:101]
	v_mfma_f32_16x16x32_bf16 v[90:93], v[140:143], v[192:195], v[90:93]
	v_mfma_f32_16x16x32_bf16 v[82:85], v[152:155], v[192:195], v[82:85]
	v_mfma_f32_16x16x32_bf16 v[74:77], v[140:143], v[200:203], v[74:77]
	v_mfma_f32_16x16x32_bf16 v[66:69], v[152:155], v[200:203], v[66:69]
	v_mfma_f32_16x16x32_bf16 v[122:125], v[148:151], v[180:183], v[122:125]
	v_mfma_f32_16x16x32_bf16 v[114:117], v[156:159], v[180:183], v[114:117]
	v_mfma_f32_16x16x32_bf16 v[106:109], v[148:151], v[188:191], v[106:109]
	v_mfma_f32_16x16x32_bf16 v[98:101], v[156:159], v[188:191], v[98:101]
	v_mfma_f32_16x16x32_bf16 v[90:93], v[148:151], v[196:199], v[90:93]
	v_mfma_f32_16x16x32_bf16 v[82:85], v[156:159], v[196:199], v[82:85]
	v_mfma_f32_16x16x32_bf16 v[74:77], v[148:151], v[204:207], v[74:77]
	v_mfma_f32_16x16x32_bf16 v[66:69], v[156:159], v[204:207], v[66:69]
	s_setprio 0
	s_setprio 1
	v_mfma_f32_16x16x32_bf16 v[126:129], v[160:163], v[176:179], v[126:129]
	v_mfma_f32_16x16x32_bf16 v[118:121], v[168:171], v[176:179], v[118:121]
	v_mfma_f32_16x16x32_bf16 v[110:113], v[160:163], v[184:187], v[110:113]
	v_mfma_f32_16x16x32_bf16 v[102:105], v[168:171], v[184:187], v[102:105]
	v_mfma_f32_16x16x32_bf16 v[94:97], v[160:163], v[192:195], v[94:97]
	v_mfma_f32_16x16x32_bf16 v[86:89], v[168:171], v[192:195], v[86:89]
	v_mfma_f32_16x16x32_bf16 v[78:81], v[160:163], v[200:203], v[78:81]
	v_mfma_f32_16x16x32_bf16 v[70:73], v[168:171], v[200:203], v[70:73]
	v_mfma_f32_16x16x32_bf16 v[126:129], v[164:167], v[180:183], v[126:129]
	v_mfma_f32_16x16x32_bf16 v[118:121], v[172:175], v[180:183], v[118:121]
	v_mfma_f32_16x16x32_bf16 v[110:113], v[164:167], v[188:191], v[110:113]
	v_mfma_f32_16x16x32_bf16 v[102:105], v[172:175], v[188:191], v[102:105]
	v_mfma_f32_16x16x32_bf16 v[94:97], v[164:167], v[196:199], v[94:97]
	v_mfma_f32_16x16x32_bf16 v[86:89], v[172:175], v[196:199], v[86:89]
	v_mfma_f32_16x16x32_bf16 v[78:81], v[164:167], v[204:207], v[78:81]
	v_mfma_f32_16x16x32_bf16 v[70:73], v[172:175], v[204:207], v[70:73]
	s_setprio 0
	s_barrier
	s_add_i32 s38, s57, s43
	v_lshl_add_u64 v[208:209], v[208:209], 0, s[98:99]
	s_mov_b32 m0, s38
	ds_read_b128 v[176:179], v147 offset:49152
	ds_read_b128 v[180:183], v147 offset:50176
	ds_read_b128 v[184:187], v147 offset:51200
	ds_read_b128 v[188:191], v147 offset:52224
	ds_read_b128 v[192:195], v147 offset:53248
	ds_read_b128 v[196:199], v147 offset:54272
	ds_read_b128 v[200:203], v147 offset:55296
	ds_read_b128 v[204:207], v147 offset:56320
	global_load_lds_dwordx4 v[208:209], off
	s_add_i32 m0, s38, 0x2000
	s_add_u32 s30, s30, 0x40080
	v_lshl_add_u64 v[208:209], v[210:211], 0, s[98:99]
	s_addc_u32 s31, s31, 0
	s_add_i32 s38, s58, s43
	global_load_lds_dwordx4 v[208:209], off
	v_lshl_add_u64 v[208:209], s[30:31], 0, v[0:1]
	s_mov_b32 m0, s38
	s_nop 0
	global_load_lds_dwordx4 v[208:209], off
	v_lshl_add_u64 v[208:209], s[30:31], 0, v[134:135]
	s_add_i32 m0, s38, 0x2000
	s_nop 0
	global_load_lds_dwordx4 v[208:209], off
	v_lshl_add_u64 v[208:209], v[212:213], 0, s[98:99]
	s_mov_b32 m0, s49
	s_nop 0
	global_load_lds_dwordx4 v[208:209], off
	v_lshl_add_u64 v[208:209], v[214:215], 0, s[98:99]
	s_mov_b32 m0, s51
	s_nop 0
	global_load_lds_dwordx4 v[208:209], off
	s_waitcnt vmcnt(8)
	s_waitcnt lgkmcnt(0)
	s_barrier
	s_setprio 1
	s_waitcnt lgkmcnt(0)
	v_mfma_f32_16x16x32_bf16 v[58:61], v[140:143], v[176:179], v[58:61]
	v_mfma_f32_16x16x32_bf16 v[50:53], v[152:155], v[176:179], v[50:53]
	v_mfma_f32_16x16x32_bf16 v[42:45], v[140:143], v[184:187], v[42:45]
	v_mfma_f32_16x16x32_bf16 v[34:37], v[152:155], v[184:187], v[34:37]
	v_mfma_f32_16x16x32_bf16 v[26:29], v[140:143], v[192:195], v[26:29]
	v_mfma_f32_16x16x32_bf16 v[18:21], v[152:155], v[192:195], v[18:21]
	v_mfma_f32_16x16x32_bf16 v[10:13], v[140:143], v[200:203], v[10:13]
	v_mfma_f32_16x16x32_bf16 v[6:9], v[152:155], v[200:203], v[6:9]
	v_mfma_f32_16x16x32_bf16 v[58:61], v[148:151], v[180:183], v[58:61]
	v_mfma_f32_16x16x32_bf16 v[50:53], v[156:159], v[180:183], v[50:53]
	v_mfma_f32_16x16x32_bf16 v[42:45], v[148:151], v[188:191], v[42:45]
	v_mfma_f32_16x16x32_bf16 v[34:37], v[156:159], v[188:191], v[34:37]
	v_mfma_f32_16x16x32_bf16 v[26:29], v[148:151], v[196:199], v[26:29]
	v_mfma_f32_16x16x32_bf16 v[18:21], v[156:159], v[196:199], v[18:21]
	v_mfma_f32_16x16x32_bf16 v[10:13], v[148:151], v[204:207], v[10:13]
	v_mfma_f32_16x16x32_bf16 v[6:9], v[156:159], v[204:207], v[6:9]
	s_setprio 0
	s_setprio 1
	v_mfma_f32_16x16x32_bf16 v[62:65], v[160:163], v[176:179], v[62:65]
	v_mfma_f32_16x16x32_bf16 v[54:57], v[168:171], v[176:179], v[54:57]
	v_mfma_f32_16x16x32_bf16 v[46:49], v[160:163], v[184:187], v[46:49]
	v_mfma_f32_16x16x32_bf16 v[38:41], v[168:171], v[184:187], v[38:41]
	v_mfma_f32_16x16x32_bf16 v[30:33], v[160:163], v[192:195], v[30:33]
	v_mfma_f32_16x16x32_bf16 v[22:25], v[168:171], v[192:195], v[22:25]
	v_mfma_f32_16x16x32_bf16 v[14:17], v[160:163], v[200:203], v[14:17]
	v_mfma_f32_16x16x32_bf16 v[2:5], v[168:171], v[200:203], v[2:5]
	v_mfma_f32_16x16x32_bf16 v[62:65], v[164:167], v[180:183], v[62:65]
	v_mfma_f32_16x16x32_bf16 v[54:57], v[172:175], v[180:183], v[54:57]
	v_mfma_f32_16x16x32_bf16 v[46:49], v[164:167], v[188:191], v[46:49]
	v_mfma_f32_16x16x32_bf16 v[38:41], v[172:175], v[188:191], v[38:41]
	v_mfma_f32_16x16x32_bf16 v[30:33], v[164:167], v[196:199], v[30:33]
	v_mfma_f32_16x16x32_bf16 v[22:25], v[172:175], v[196:199], v[22:25]
	v_mfma_f32_16x16x32_bf16 v[14:17], v[164:167], v[204:207], v[14:17]
	v_mfma_f32_16x16x32_bf16 v[2:5], v[172:175], v[204:207], v[2:5]
	s_setprio 0
	s_barrier
	s_add_i32 s56, s56, 2
	s_add_u32 s28, s28, 0x100
	s_addc_u32 s29, s29, 0
	s_add_u32 s54, s54, 0x100
	s_addc_u32 s55, s55, 0
	s_cmp_gt_u32 s56, 13
	s_cbranch_scc1 .Lpeel_done_374

.Lpeel_done_374:
	s_and_b64 vcc, exec, s[12:13]
	s_cbranch_vccz .LBB0_377
	s_barrier
